# DOWN tail k-loop: fragments read first, DMA address block interleaved with the 8 MFMAs (was run by all waves in lockstep ahead of the reads)
# speedup vs baseline: 1.0570x; 1.0061x over previous
;     ...
;     auto issue_at = [&](int mm0, int nn0, int kt, int buf) {
;       char* lb = L0 + buf * BUFB;
; #pragma unroll
;       for (int i = 0; i < 4; ++i) {
;         const int seg = wv * 4 + i, row = seg * 8 + gl_row;
;         const int c = (lane & 7) ^ ((row >> 1) & 7);
;         const u16* ap = (kt < g.split) ? g.a0 + (size_t)(mm0 + row) * g.ld0 + kt * g.ks0 : g.a1 + (size_t)(mm0 + row) * g.ld1 + (kt - g.split) * 64;
;         __builtin_amdgcn_global_load_lds((const unsigned*)(ap + c * 8), (__attribute__((address_space(3))) unsigned*)(lb + seg * 1024 + lane * 16), 16, 0, 0);
;       }
; #pragma unroll
;       for (int i = 0; i < BN / 64; ++i) {
;         const int seg = wv * (BN / 64) + i, row = seg * 8 + gl_row;
;         const int c = (lane & 7) ^ ((row >> 1) & 7);
;         __builtin_amdgcn_global_load_lds((const unsigned*)(g.W + (size_t)(nn0 + row) * g.K + kt * 64 + c * 8),
;                                          (__attribute__((address_space(3))) unsigned*)(lb + 256 * 128 + seg * 1024 + lane * 16), 16, 0, 0);
;       }
;     };
;     auto issue = [&](int kt, int buf) { issue_at(m0, n0, kt, buf); };
;     auto compute2 = [&](int buf) {
;       const char* lb = L0 + buf * BUFB;
; #pragma unroll
;       for (int ks = 0; ks < 4; ++ks) {
;         const int c = ks * 2 + hh;
;         bf16x8 wf[2], xf[MI];
; #pragma unroll
;         for (int j = 0; j < 2; ++j) { const int r = wn * 64 + j * 32 + l32; wf[j] = *(const bf16x8*)(lb + 256 * 128 + r * 128 + ((c ^ ((r >> 1) & 7)) << 4)); }
; #pragma unroll
;         for (int i = 0; i < MI; ++i) { const int r = wm * (MI * 32) + i * 32 + l32; xf[i] = *(const bf16x8*)(lb + r * 128 + ((c ^ ((r >> 1) & 7)) << 4)); }
; #pragma unroll
;         for (int i = 0; i < MI; ++i) {
;           acc[i][0] = MFMA(wf[0], xf[i], acc[i][0]);
;           acc[i][1] = MFMA(wf[1], xf[i], acc[i][1]);
;         }
;     ...
;       for (int kt = 0; kt < nk; ++kt) {
;         const int b2 = buf == 0 ? 2 : buf - 1;
;         if (kt + 2 < nk) issue(kt + 2, b2);
;         compute2(buf);
;         if (kt + 2 < nk) { if (BN == 128) asm volatile("s_waitcnt vmcnt(6)" ::: "memory"); else asm volatile("s_waitcnt vmcnt(5)" ::: "memory"); }
;         else asm volatile("s_waitcnt vmcnt(0)" ::: "memory");
;         asm volatile("s_waitcnt lgkmcnt(0)" ::: "memory");
;         __builtin_amdgcn_s_barrier();
;         buf = buf == 2 ? 0 : buf + 1;
;       }
.LBB0_1292:
	s_andn2_b64 vcc, exec, s[52:53]
	s_cbranch_vccnz .LBB0_1294
	v_add_u32_e32 v53, s58, v69
	v_add_u32_e32 v55, v53, v68
	ds_read_b128 v[82:85], v55 offset:32768
	v_add_u32_e32 v57, v53, v62
	v_add_u32_e32 v73, v57, v68
	ds_read_b128 v[86:89], v73
	v_add_u32_e32 v73, v57, v70
	ds_read_b128 v[90:93], v55 offset:36864
	v_add_u32_e32 v55, v53, v70
	ds_read_b128 v[94:97], v55 offset:32768
	ds_read_b128 v[98:101], v73
	v_add_u32_e32 v73, v57, v71
	ds_read_b128 v[102:105], v55 offset:36864
	v_add_u32_e32 v55, v53, v71
	v_add_u32_e32 v53, v53, v72
	ds_read_b128 v[106:109], v55 offset:32768
	ds_read_b128 v[110:113], v73
	ds_read_b128 v[114:117], v55 offset:36864
	v_add_u32_e32 v55, v57, v72
	ds_read_b128 v[118:121], v53 offset:32768
	ds_read_b128 v[122:125], v55
	ds_read_b128 v[126:129], v53 offset:36864
	s_waitcnt lgkmcnt(10)
	v_mfma_f32_32x32x16_bf16 v[18:33], v[82:85], v[86:89], v[18:33]
	s_add_i32 s52, s58, 0xffff6000
	s_cmp_lg_u32 s15, 0
	s_cselect_b32 s52, s52, 0x14000
	s_add_i32 s52, s52, 0
	s_cmp_lt_u32 s57, 20
	v_lshl_add_u64 v[74:75], v[50:51], 0, s[16:17]
	v_lshl_add_u64 v[76:77], v[42:43], 0, s[16:17]
	s_waitcnt lgkmcnt(9)
	v_mfma_f32_32x32x16_bf16 v[2:17], v[90:93], v[86:89], v[2:17]
	s_cselect_b64 vcc, -1, 0
	v_add3_u32 v53, s52, v62, v63
	v_cndmask_b32_e32 v75, v77, v75, vcc
	v_cndmask_b32_e32 v74, v76, v74, vcc
	v_readfirstlane_b32 s53, v53
	v_lshl_add_u64 v[74:75], v[74:75], 0, v[0:1]
	s_mov_b32 m0, s53
	s_waitcnt lgkmcnt(7)
	v_mfma_f32_32x32x16_bf16 v[18:33], v[94:97], v[98:101], v[18:33]
	v_lshl_add_u64 v[76:77], v[44:45], 0, s[16:17]
	global_load_lds_dwordx4 v[74:75], off
	v_lshl_add_u64 v[74:75], v[40:41], 0, s[16:17]
	v_cndmask_b32_e32 v75, v77, v75, vcc
	v_cndmask_b32_e32 v74, v76, v74, vcc
	v_mov_b32_e32 v53, v1
	v_lshl_add_u64 v[74:75], v[74:75], 0, v[52:53]
	s_waitcnt lgkmcnt(6)
	v_mfma_f32_32x32x16_bf16 v[2:17], v[102:105], v[98:101], v[2:17]
	v_add3_u32 v53, s52, v64, v63
	v_lshl_add_u64 v[76:77], v[46:47], 0, s[16:17]
	v_readfirstlane_b32 s53, v53
	s_mov_b32 m0, s53
	v_add3_u32 v53, s52, v65, v63
	global_load_lds_dwordx4 v[74:75], off
	v_lshl_add_u64 v[74:75], v[38:39], 0, s[16:17]
	s_waitcnt lgkmcnt(4)
	v_mfma_f32_32x32x16_bf16 v[18:33], v[106:109], v[110:113], v[18:33]
	v_cndmask_b32_e32 v75, v77, v75, vcc
	v_cndmask_b32_e32 v74, v76, v74, vcc
	v_mov_b32_e32 v55, v1
	v_readfirstlane_b32 s53, v53
	v_lshl_add_u64 v[74:75], v[74:75], 0, v[54:55]
	s_mov_b32 m0, s53
	v_add3_u32 v53, s52, v66, v63
	s_waitcnt lgkmcnt(3)
	v_mfma_f32_32x32x16_bf16 v[2:17], v[114:117], v[110:113], v[2:17]
	global_load_lds_dwordx4 v[74:75], off
	v_lshl_add_u64 v[74:75], v[36:37], 0, s[16:17]
	v_lshl_add_u64 v[76:77], v[48:49], 0, s[16:17]
	v_readfirstlane_b32 s53, v53
	v_add_u32_e32 v53, s52, v67
	v_cndmask_b32_e32 v75, v77, v75, vcc
	v_cndmask_b32_e32 v74, v76, v74, vcc
	s_waitcnt lgkmcnt(1)
	v_mfma_f32_32x32x16_bf16 v[18:33], v[118:121], v[122:125], v[18:33]
	v_mov_b32_e32 v57, v1
	v_add3_u32 v53, v53, v63, s89
	v_lshl_add_u64 v[74:75], v[74:75], 0, v[56:57]
	s_mov_b32 m0, s53
	v_readfirstlane_b32 s52, v53
	global_load_lds_dwordx4 v[74:75], off
	v_lshl_add_u64 v[74:75], v[34:35], 0, s[16:17]
	s_waitcnt lgkmcnt(0)
	v_mfma_f32_32x32x16_bf16 v[2:17], v[126:129], v[122:125], v[2:17]
	s_mov_b32 m0, s52
	s_mov_b32 s59, s58
	global_load_lds_dwordx4 v[74:75], off
	s_mov_b64 s[52:53], -1
	s_and_b64 vcc, exec, s[50:51]
	s_branch .Ldtail_join

;     ...
;         if (kt + 2 < nk) { if (BN == 128) asm volatile("s_waitcnt vmcnt(6)" ::: "memory"); else asm volatile("s_waitcnt vmcnt(5)" ::: "memory"); }
;         else asm volatile("s_waitcnt vmcnt(0)" ::: "memory");
;         asm volatile("s_waitcnt lgkmcnt(0)" ::: "memory");
;         __builtin_amdgcn_s_barrier();
.Ldtail_join:
	s_cbranch_vccz .LBB0_1296
	s_waitcnt vmcnt(0)
	s_mov_b64 s[52:53], 0
